# sample-scan token shift: mu loads issued with the current-row load (one round trip per iteration)
# speedup vs baseline: 1.0023x; 1.0023x over previous
; __device__ __forceinline__ void unpack8(u32x4 u, float* f) { f[0] = bflo(u.x); f[1] = bfhi(u.x); f[2] = bflo(u.y); f[3] = bfhi(u.y); f[4] = bflo(u.z); f[5] = bfhi(u.z); f[6] = bflo(u.w); f[7] = bfhi(u.w); }
; __device__ __forceinline__ void sscan_item(const Args& A, LAS unsigned char* lds, int tid, int lane, int wave, int bg, int h) {
;     ...
;                 const int bi = t >> 3, tt = t & 7, b = bg * 4 + bi; const float* shift0 = A.st_shift + (size_t)b * SHIFT;
;                 const int zcol = (s == 0 ? h * 64 : s == 1 ? 512 + h * 64 : s == 2 ? 1024 + h * 64 : s == 3 ? 1536 : 1600) + within;
;                 const size_t row = (size_t)MP + (size_t)b * 8 + tt;
;                 float cur[8], prv[8]; unpack8(*(const u32x4*)(Z + row * NZ + zcol), cur);
;                 if (tt == 0) {
;                     { const f32x4 p0 = *(const f32x4*)(shift0 + zcol), p1 = *(const f32x4*)(shift0 + zcol + 4);
;                         prv[0] = p0.x; prv[1] = p0.y; prv[2] = p0.z; prv[3] = p0.w; prv[4] = p1.x; prv[5] = p1.y; prv[6] = p1.z; prv[7] = p1.w; }
;                 } else unpack8(*(const u32x4*)(Z + (row - 1) * NZ + zcol), prv);
;                 const f32x4 m0 = *(const f32x4*)(A.mu + zcol), m1 = *(const f32x4*)(A.mu + zcol + 4);
;                 const float mu[8] = {m0.x, m0.y, m0.z, m0.w, m1.x, m1.y, m1.z, m1.w};
; #pragma unroll
;                 for (int i = 0; i < 8; ++i) { float v = cur[i] + mu[i] * (prv[i] - cur[i]); if (s == 3) v = tanhf(v); o[i] = v; }
.LBB0_334:
	s_or_b64 exec, exec, s[8:9]
	v_and_b32_e32 v201, 0xffff, v48
	v_lshlrev_b32_e32 v48, 3, v49
	v_and_b32_e32 v202, 56, v48
	v_lshrrev_b32_e32 v48, 3, v201
	v_add_u32_e32 v56, s64, v48
	v_ashrrev_i32_e32 v57, 31, v56
	v_and_b32_e32 v54, 7, v201
	v_lshlrev_b64 v[48:49], 3, v[56:57]
	v_or_b32_e32 v48, v48, v54
	s_mov_b64 s[8:9], 0x8000
	v_add_u32_e32 v58, v50, v202
	v_lshl_add_u64 v[48:49], v[48:49], 0, s[8:9]
	v_mov_b64_e32 v[50:51], s[94:95]
	v_mad_u64_u32 v[50:51], s[8:9], v48, s52, v[50:51]
	v_mad_i32_i24 v51, v49, s52, v51
	v_lshlrev_b32_e32 v76, 1, v58
	v_lshl_add_u64 v[52:53], v[50:51], 0, v[76:77]
	global_load_dwordx4 v[48:51], v[52:53], off
	v_lshlrev_b32_e32 v76, 2, v58
	global_load_dwordx4 v[68:71], v76, s[60:61]
	global_load_dwordx4 v[60:63], v76, s[60:61] offset:16
	v_cmp_ne_u32_e32 vcc, 0, v54
	s_and_saveexec_b64 s[8:9], vcc
	s_xor_b64 s[8:9], exec, s[8:9]
	s_cbranch_execz .LBB0_336
	v_add_co_u32_e32 v52, vcc, 0xfffff000, v52
	s_nop 1
	v_addc_co_u32_e32 v53, vcc, -1, v53, vcc
	global_load_dwordx4 v[52:55], v[52:53], off offset:-3072
	s_waitcnt vmcnt(0)
	v_lshlrev_b32_e32 v64, 16, v52
	v_and_b32_e32 v65, 0xffff0000, v52
	v_lshlrev_b32_e32 v66, 16, v53
	v_and_b32_e32 v67, 0xffff0000, v53
	v_lshlrev_b32_e32 v52, 16, v54
	v_and_b32_e32 v53, 0xffff0000, v54
	v_lshlrev_b32_e32 v54, 16, v55
	v_and_b32_e32 v55, 0xffff0000, v55

; __device__ __forceinline__ void sscan_item(const Args& A, LAS unsigned char* lds, int tid, int lane, int wave, int bg, int h) {
;     ...
;                 const f32x4 m0 = *(const f32x4*)(A.mu + zcol), m1 = *(const f32x4*)(A.mu + zcol + 4);
;                 const float mu[8] = {m0.x, m0.y, m0.z, m0.w, m1.x, m1.y, m1.z, m1.w};
; #pragma unroll
;                 for (int i = 0; i < 8; ++i) { float v = cur[i] + mu[i] * (prv[i] - cur[i]); if (s == 3) v = tanhf(v); o[i] = v; }
.LBB0_338:
	s_or_b64 exec, exec, s[8:9]
	s_waitcnt vmcnt(0)
	v_lshlrev_b32_e32 v56, 16, v48
	v_sub_f32_e32 v57, v64, v56
	v_cmp_eq_u32_e32 vcc, 3, v200
	s_waitcnt vmcnt(1)
	v_fmac_f32_e32 v56, v57, v68
	s_and_saveexec_b64 s[26:27], vcc
	s_cbranch_execz .LBB0_344
	v_cmp_nlt_f32_e64 s[8:9], |v56|, s54
	s_and_saveexec_b64 s[28:29], s[8:9]
	s_xor_b64 s[28:29], exec, s[28:29]
	s_cbranch_execz .LBB0_341
	v_add_f32_e64 v57, |v56|, |v56|
	v_mul_f32_e32 v58, 0x3fb8aa3b, v57
	v_rndne_f32_e32 v59, v58
	v_sub_f32_e32 v64, v58, v59
	v_fma_f32 v58, v57, s55, -v58
	v_fmac_f32_e32 v58, 0x32a5705f, v57
	v_add_f32_e32 v58, v64, v58
	v_cvt_i32_f32_e32 v59, v59
	v_exp_f32_e32 v58, v58
	v_cmp_ngt_f32_e64 s[8:9], s56, v57
	v_ldexp_f32 v58, v58, v59
	s_nop 0
	v_cndmask_b32_e64 v58, 0, v58, s[8:9]
	v_cmp_nlt_f32_e64 s[8:9], s57, v57
	s_nop 1
	v_cndmask_b32_e64 v57, v192, v58, s[8:9]
	v_add_f32_e32 v57, 1.0, v57
	v_rcp_f32_e32 v57, v57
	s_nop 0
	v_fma_f32 v57, v57, -2.0, 1.0
